# weight conversion back-end: output-row store addresses chained with 64-bit adds instead of per-store 64-bit multiplies (4 sites)
# speedup vs baseline: 1.0051x; 1.0051x over previous
; #define LAS __attribute__((address_space(3)))
; __device__ __forceinline__ unsigned pk2(float lo, float hi) { unsigned r; asm("v_cvt_pk_bf16_f32 %0, %1, %2" : "=v"(r) : "v"(lo), "v"(hi)); return r; }
; #define LDS_WAIT() asm volatile("s_waitcnt lgkmcnt(0)" ::: "memory")
; __device__ __forceinline__ void p0_item(const float* W, const float* gain, int K, int N, bf16_t* WT, int mode, LAS float* scr, int item, int lane) {
;     ...
;     for (int i = 0; i < 16; ++i) { LAS float* s = scr + (4 * i + kr) * 65 + nc; s[0] = v[i][0]; s[1] = v[i][1]; s[2] = v[i][2]; s[3] = v[i][3]; }
;     LDS_WAIT();
;     const int c = lane & 7;
;     const int rbase = (mode == 0) ? n0 : ((n0 >> 7) * 256 + (mode == 2 ? 128 : 0) + (n0 & 127));
; #pragma unroll
;     for (int j = 0; j < 8; ++j) { const int n = (lane >> 3) + 8 * j; const LAS float* s = scr + (8 * c) * 65 + n;
;         u32x4 o; o.x = pk2(s[0 * 65], s[1 * 65]); o.y = pk2(s[2 * 65], s[3 * 65]); o.z = pk2(s[4 * 65], s[5 * 65]); o.w = pk2(s[6 * 65], s[7 * 65]);
;         __builtin_nontemporal_store(o, (u32x4*)(WT + (size_t)(rbase + n) * K + k0 + 8 * c)); }
.LBB0_105:
	s_or_b64 exec, exec, s[8:9]
	s_waitcnt vmcnt(15)
	ds_write2_b32 v92, v6, v7 offset1:1
	ds_write2_b32 v92, v8, v9 offset0:2 offset1:3
	v_add_u32_e32 v6, 0x410, v92
	s_waitcnt vmcnt(14)
	ds_write2_b32 v6, v2, v3 offset1:1
	v_add_u32_e32 v2, 0x418, v92
	ds_write2_b32 v2, v4, v5 offset1:1
	v_add_u32_e32 v2, 0x820, v92
	s_waitcnt vmcnt(13)
	ds_write2_b32 v2, v14, v15 offset1:1
	v_add_u32_e32 v2, 0x828, v92
	ds_write2_b32 v2, v16, v17 offset1:1
	v_add_u32_e32 v2, 0xc30, v92
	s_waitcnt vmcnt(12)
	ds_write2_b32 v2, v10, v11 offset1:1
	v_add_u32_e32 v2, 0xc38, v92
	ds_write2_b32 v2, v12, v13 offset1:1
	v_add_u32_e32 v2, 0x1040, v92
	s_waitcnt vmcnt(11)
	ds_write2_b32 v2, v22, v23 offset1:1
	v_add_u32_e32 v2, 0x1048, v92
	ds_write2_b32 v2, v24, v25 offset1:1
	v_add_u32_e32 v2, 0x1450, v92
	s_waitcnt vmcnt(10)
	ds_write2_b32 v2, v18, v19 offset1:1
	v_add_u32_e32 v2, 0x1458, v92
	ds_write2_b32 v2, v20, v21 offset1:1
	v_add_u32_e32 v2, 0x1860, v92
	s_waitcnt vmcnt(9)
	ds_write2_b32 v2, v30, v31 offset1:1
	v_add_u32_e32 v2, 0x1868, v92
	ds_write2_b32 v2, v32, v33 offset1:1
	v_add_u32_e32 v2, 0x1c70, v92
	s_waitcnt vmcnt(8)
	ds_write2_b32 v2, v26, v27 offset1:1
	v_add_u32_e32 v2, 0x1c78, v92
	ds_write2_b32 v2, v28, v29 offset1:1
	v_add_u32_e32 v2, 0x2080, v92
	s_waitcnt vmcnt(7)
	ds_write2_b32 v2, v38, v39 offset1:1
	v_add_u32_e32 v2, 0x2088, v92
	ds_write2_b32 v2, v40, v41 offset1:1
	v_add_u32_e32 v2, 0x2490, v92
	s_waitcnt vmcnt(6)
	ds_write2_b32 v2, v34, v35 offset1:1
	v_add_u32_e32 v2, 0x2498, v92
	ds_write2_b32 v2, v36, v37 offset1:1
	v_add_u32_e32 v2, 0x28a0, v92
	s_waitcnt vmcnt(5)
	ds_write2_b32 v2, v46, v47 offset1:1
	v_add_u32_e32 v2, 0x28a8, v92
	ds_write2_b32 v2, v48, v49 offset1:1
	v_add_u32_e32 v2, 0x2cb0, v92
	s_waitcnt vmcnt(4)
	ds_write2_b32 v2, v42, v43 offset1:1
	v_add_u32_e32 v2, 0x2cb8, v92
	ds_write2_b32 v2, v44, v45 offset1:1
	v_add_u32_e32 v2, 0x30c0, v92
	s_waitcnt vmcnt(3)
	ds_write2_b32 v2, v54, v55 offset1:1
	v_add_u32_e32 v2, 0x30c8, v92
	ds_write2_b32 v2, v56, v57 offset1:1
	v_add_u32_e32 v2, 0x34d0, v92
	s_waitcnt vmcnt(2)
	ds_write2_b32 v2, v50, v51 offset1:1
	v_add_u32_e32 v2, 0x34d8, v92
	ds_write2_b32 v2, v52, v53 offset1:1
	v_add_u32_e32 v2, 0x38e0, v92
	s_waitcnt vmcnt(1)
	ds_write2_b32 v2, v62, v63 offset1:1
	v_add_u32_e32 v2, 0x38e8, v92
	ds_write2_b32 v2, v64, v65 offset1:1
	v_add_u32_e32 v2, 0x3cf0, v92
	s_waitcnt vmcnt(0)
	ds_write2_b32 v2, v58, v59 offset1:1
	v_add_u32_e32 v2, 0x3cf8, v92
	ds_write2_b32 v2, v60, v61 offset1:1
	s_waitcnt lgkmcnt(0)
	v_lshlrev_b32_e32 v2, 7, v73
	v_and_b32_e32 v2, 0xffffff00, v2
	v_and_b32_e32 v3, 64, v74
	ds_read2_b32 v[6:7], v83 offset0:65 offset1:73
	ds_read2_b32 v[8:9], v83 offset1:8
	ds_read2_b32 v[10:11], v83 offset0:130 offset1:138
	ds_read2_b32 v[12:13], v83 offset0:195 offset1:203
	v_lshl_add_u64 v[70:71], s[80:81], 0, v[70:71]
	v_or3_b32 v2, v2, v67, v3
	v_ashrrev_i32_e32 v73, 31, v72
	v_cndmask_b32_e64 v26, v2, v74, s[6:7]
	v_lshl_add_u64 v[2:3], v[72:73], 1, v[70:71]
	v_mov_b32_e32 v67, v1
	v_add_u32_e32 v27, 0x400, v83
	ds_read2_b32 v[14:15], v27 offset0:4 offset1:12
	ds_read2_b32 v[16:17], v27 offset0:69 offset1:77
	ds_read2_b32 v[18:19], v27 offset0:134 offset1:142
	ds_read2_b32 v[20:21], v27 offset0:199 offset1:207
	v_lshl_add_u64 v[22:23], v[2:3], 0, v[66:67]
	s_waitcnt lgkmcnt(6)
	v_cvt_pk_bf16_f32 v2, v8, v6
	v_or_b32_e32 v6, v26, v82
	v_mul_lo_u32 v8, v69, v6
	v_mad_u64_u32 v[24:25], s[6:7], v68, v6, 0
	v_ashrrev_i32_e32 v6, 31, v26
	v_mul_lo_u32 v28, v68, v6
	v_add3_u32 v25, v25, v28, v8
	v_lshl_add_u64 v[24:25], v[24:25], 1, v[22:23]
	v_lshlrev_b64 v[128:129], 4, v[68:69]
	v_lshl_add_u64 v[126:127], v[24:25], 0, v[128:129]
	s_waitcnt lgkmcnt(4)
; #define LAS __attribute__((address_space(3)))
; __device__ __forceinline__ unsigned pk2(float lo, float hi) { unsigned r; asm("v_cvt_pk_bf16_f32 %0, %1, %2" : "=v"(r) : "v"(lo), "v"(hi)); return r; }
; __device__ __forceinline__ void p0_item(const float* W, const float* gain, int K, int N, bf16_t* WT, int mode, LAS float* scr, int item, int lane) {
;     ...
;     for (int j = 0; j < 8; ++j) { const int n = (lane >> 3) + 8 * j; const LAS float* s = scr + (8 * c) * 65 + n;
;         u32x4 o; o.x = pk2(s[0 * 65], s[1 * 65]); o.y = pk2(s[2 * 65], s[3 * 65]); o.z = pk2(s[4 * 65], s[5 * 65]); o.w = pk2(s[6 * 65], s[7 * 65]);
;         __builtin_nontemporal_store(o, (u32x4*)(WT + (size_t)(rbase + n) * K + k0 + 8 * c)); }
	v_cvt_pk_bf16_f32 v3, v10, v12
	s_waitcnt lgkmcnt(2)
	v_cvt_pk_bf16_f32 v4, v14, v16
	s_waitcnt lgkmcnt(0)
	v_cvt_pk_bf16_f32 v5, v18, v20
	global_store_dwordx4 v[24:25], v[2:5], off nt
	s_nop 1
	s_nop 0
	v_cvt_pk_bf16_f32 v2, v9, v7
	v_cvt_pk_bf16_f32 v3, v11, v13
	v_cvt_pk_bf16_f32 v4, v15, v17
	v_cvt_pk_bf16_f32 v5, v19, v21
	ds_read2_b32 v[8:9], v83 offset0:16 offset1:24
	ds_read2_b32 v[10:11], v83 offset0:81 offset1:89
	ds_read2_b32 v[12:13], v83 offset0:146 offset1:154
	ds_read2_b32 v[14:15], v83 offset0:211 offset1:219
	ds_read2_b32 v[16:17], v27 offset0:20 offset1:28
	ds_read2_b32 v[18:19], v27 offset0:85 offset1:93
	ds_read2_b32 v[20:21], v27 offset0:150 offset1:158
	ds_read2_b32 v[24:25], v27 offset0:215 offset1:223
	global_store_dwordx4 v[126:127], v[2:5], off nt
	v_lshl_add_u64 v[126:127], v[126:127], 0, v[128:129]
	s_waitcnt lgkmcnt(6)
	v_cvt_pk_bf16_f32 v2, v8, v10
	s_waitcnt lgkmcnt(4)
	v_cvt_pk_bf16_f32 v3, v12, v14
	s_waitcnt lgkmcnt(2)
	v_cvt_pk_bf16_f32 v4, v16, v18
	s_waitcnt lgkmcnt(0)
	v_cvt_pk_bf16_f32 v5, v20, v24
	global_store_dwordx4 v[126:127], v[2:5], off nt
	s_nop 1
	v_lshl_add_u64 v[126:127], v[126:127], 0, v[128:129]
	v_cvt_pk_bf16_f32 v2, v9, v11
	v_cvt_pk_bf16_f32 v3, v13, v15
	v_cvt_pk_bf16_f32 v4, v17, v19
	v_cvt_pk_bf16_f32 v5, v21, v25
	ds_read2_b32 v[8:9], v83 offset0:32 offset1:40
	ds_read2_b32 v[10:11], v83 offset0:97 offset1:105
	ds_read2_b32 v[12:13], v83 offset0:162 offset1:170
	ds_read2_b32 v[14:15], v83 offset0:227 offset1:235
	ds_read2_b32 v[16:17], v27 offset0:36 offset1:44
	ds_read2_b32 v[18:19], v27 offset0:101 offset1:109
	ds_read2_b32 v[20:21], v27 offset0:166 offset1:174
	ds_read2_b32 v[24:25], v27 offset0:231 offset1:239
	global_store_dwordx4 v[126:127], v[2:5], off nt
	v_lshl_add_u64 v[126:127], v[126:127], 0, v[128:129]
	s_waitcnt lgkmcnt(6)
	v_cvt_pk_bf16_f32 v2, v8, v10
	s_waitcnt lgkmcnt(4)
	v_cvt_pk_bf16_f32 v3, v12, v14
	s_waitcnt lgkmcnt(2)
	v_cvt_pk_bf16_f32 v4, v16, v18
	s_waitcnt lgkmcnt(0)
	v_cvt_pk_bf16_f32 v5, v20, v24
	global_store_dwordx4 v[126:127], v[2:5], off nt
	s_nop 1
	v_lshl_add_u64 v[126:127], v[126:127], 0, v[128:129]
	v_cvt_pk_bf16_f32 v2, v9, v11
	v_cvt_pk_bf16_f32 v3, v13, v15
	v_cvt_pk_bf16_f32 v4, v17, v19
	v_cvt_pk_bf16_f32 v5, v21, v25
	ds_read2_b32 v[8:9], v83 offset0:48 offset1:56
	ds_read2_b32 v[10:11], v83 offset0:113 offset1:121
	ds_read2_b32 v[12:13], v83 offset0:178 offset1:186
	ds_read2_b32 v[14:15], v83 offset0:243 offset1:251
	ds_read2_b32 v[16:17], v27 offset0:52 offset1:60
	ds_read2_b32 v[18:19], v27 offset0:117 offset1:125
	ds_read2_b32 v[20:21], v27 offset0:182 offset1:190
	ds_read2_b32 v[24:25], v27 offset0:247 offset1:255
	global_store_dwordx4 v[126:127], v[2:5], off nt
	v_lshl_add_u64 v[126:127], v[126:127], 0, v[128:129]
	s_waitcnt lgkmcnt(6)
	v_cvt_pk_bf16_f32 v2, v8, v10
	s_waitcnt lgkmcnt(4)
	v_cvt_pk_bf16_f32 v3, v12, v14
	s_waitcnt lgkmcnt(2)
	v_cvt_pk_bf16_f32 v4, v16, v18
	s_waitcnt lgkmcnt(0)
	v_cvt_pk_bf16_f32 v5, v20, v24
	global_store_dwordx4 v[126:127], v[2:5], off nt
	v_lshl_add_u64 v[126:127], v[126:127], 0, v[128:129]
	v_readlane_b32 s6, v254, 53
	v_cvt_pk_bf16_f32 v2, v9, v11
	v_cvt_pk_bf16_f32 v3, v13, v15
	v_cvt_pk_bf16_f32 v4, v17, v19
	v_cvt_pk_bf16_f32 v5, v21, v25
	global_store_dwordx4 v[126:127], v[2:5], off nt
	s_nop 0
	v_add_u32_e32 v91, s6, v91
	s_waitcnt lgkmcnt(0)
	s_movk_i32 s7, 0x35ff
	v_add_u32_e32 v2, 0x2100, v91
	v_cmp_lt_i32_e32 vcc, s7, v2
	s_or_b64 s[4:5], vcc, s[4:5]
	v_add_u32_e32 v80, s6, v80
	s_andn2_b64 exec, exec, s[4:5]
	s_cbranch_execz .LBB0_116

; #define LAS __attribute__((address_space(3)))
; __device__ __forceinline__ unsigned pk2(float lo, float hi) { unsigned r; asm("v_cvt_pk_bf16_f32 %0, %1, %2" : "=v"(r) : "v"(lo), "v"(hi)); return r; }
; #define LDS_WAIT() asm volatile("s_waitcnt lgkmcnt(0)" ::: "memory")
; __device__ __forceinline__ void p0_item(const float* W, const float* gain, int K, int N, bf16_t* WT, int mode, LAS float* scr, int item, int lane) {
;     ...
;     for (int i = 0; i < 16; ++i) { LAS float* s = scr + (4 * i + kr) * 65 + nc; s[0] = v[i][0]; s[1] = v[i][1]; s[2] = v[i][2]; s[3] = v[i][3]; }
;     LDS_WAIT();
;     const int c = lane & 7;
;     const int rbase = (mode == 0) ? n0 : ((n0 >> 7) * 256 + (mode == 2 ? 128 : 0) + (n0 & 127));
; #pragma unroll
;     for (int j = 0; j < 8; ++j) { const int n = (lane >> 3) + 8 * j; const LAS float* s = scr + (8 * c) * 65 + n;
;         u32x4 o; o.x = pk2(s[0 * 65], s[1 * 65]); o.y = pk2(s[2 * 65], s[3 * 65]); o.z = pk2(s[4 * 65], s[5 * 65]); o.w = pk2(s[6 * 65], s[7 * 65]);
;         __builtin_nontemporal_store(o, (u32x4*)(WT + (size_t)(rbase + n) * K + k0 + 8 * c)); }
.LBB0_316:
	s_or_b64 exec, exec, s[10:11]
	s_waitcnt vmcnt(15)
	ds_write2_b32 v91, v6, v7 offset1:1
	ds_write2_b32 v91, v8, v9 offset0:2 offset1:3
	v_add_u32_e32 v6, 0x410, v91
	s_waitcnt vmcnt(14)
	ds_write2_b32 v6, v2, v3 offset1:1
	v_add_u32_e32 v2, 0x418, v91
	ds_write2_b32 v2, v4, v5 offset1:1
	v_add_u32_e32 v2, 0x820, v91
	s_waitcnt vmcnt(13)
	ds_write2_b32 v2, v14, v15 offset1:1
	v_add_u32_e32 v2, 0x828, v91
	ds_write2_b32 v2, v16, v17 offset1:1
	v_add_u32_e32 v2, 0xc30, v91
	s_waitcnt vmcnt(12)
	ds_write2_b32 v2, v10, v11 offset1:1
	v_add_u32_e32 v2, 0xc38, v91
	ds_write2_b32 v2, v12, v13 offset1:1
	v_add_u32_e32 v2, 0x1040, v91
	s_waitcnt vmcnt(11)
	ds_write2_b32 v2, v22, v23 offset1:1
	v_add_u32_e32 v2, 0x1048, v91
	ds_write2_b32 v2, v24, v25 offset1:1
	v_add_u32_e32 v2, 0x1450, v91
	s_waitcnt vmcnt(10)
	ds_write2_b32 v2, v18, v19 offset1:1
	v_add_u32_e32 v2, 0x1458, v91
	ds_write2_b32 v2, v20, v21 offset1:1
	v_add_u32_e32 v2, 0x1860, v91
	s_waitcnt vmcnt(9)
	ds_write2_b32 v2, v30, v31 offset1:1
	v_add_u32_e32 v2, 0x1868, v91
	ds_write2_b32 v2, v32, v33 offset1:1
	v_add_u32_e32 v2, 0x1c70, v91
	s_waitcnt vmcnt(8)
	ds_write2_b32 v2, v26, v27 offset1:1
	v_add_u32_e32 v2, 0x1c78, v91
	ds_write2_b32 v2, v28, v29 offset1:1
	v_add_u32_e32 v2, 0x2080, v91
	s_waitcnt vmcnt(7)
	ds_write2_b32 v2, v38, v39 offset1:1
	v_add_u32_e32 v2, 0x2088, v91
	ds_write2_b32 v2, v40, v41 offset1:1
	v_add_u32_e32 v2, 0x2490, v91
	s_waitcnt vmcnt(6)
	ds_write2_b32 v2, v34, v35 offset1:1
	v_add_u32_e32 v2, 0x2498, v91
	ds_write2_b32 v2, v36, v37 offset1:1
	v_add_u32_e32 v2, 0x28a0, v91
	s_waitcnt vmcnt(5)
	ds_write2_b32 v2, v46, v47 offset1:1
	v_add_u32_e32 v2, 0x28a8, v91
	ds_write2_b32 v2, v48, v49 offset1:1
	v_add_u32_e32 v2, 0x2cb0, v91
	s_waitcnt vmcnt(4)
	ds_write2_b32 v2, v42, v43 offset1:1
	v_add_u32_e32 v2, 0x2cb8, v91
	ds_write2_b32 v2, v44, v45 offset1:1
	v_add_u32_e32 v2, 0x30c0, v91
	s_waitcnt vmcnt(3)
	ds_write2_b32 v2, v54, v55 offset1:1
	v_add_u32_e32 v2, 0x30c8, v91
	ds_write2_b32 v2, v56, v57 offset1:1
	v_add_u32_e32 v2, 0x34d0, v91
	s_waitcnt vmcnt(2)
	ds_write2_b32 v2, v50, v51 offset1:1
	v_add_u32_e32 v2, 0x34d8, v91
	ds_write2_b32 v2, v52, v53 offset1:1
	v_add_u32_e32 v2, 0x38e0, v91
	s_waitcnt vmcnt(1)
	ds_write2_b32 v2, v62, v63 offset1:1
	v_add_u32_e32 v2, 0x38e8, v91
	ds_write2_b32 v2, v64, v65 offset1:1
	v_add_u32_e32 v2, 0x3cf0, v91
	s_waitcnt vmcnt(0)
	ds_write2_b32 v2, v58, v59 offset1:1
	v_add_u32_e32 v2, 0x3cf8, v91
	ds_write2_b32 v2, v60, v61 offset1:1
	v_cndmask_b32_e32 v72, 0, v228, vcc
	v_mov_b32_e32 v73, v1
	s_waitcnt lgkmcnt(0)
	v_lshlrev_b32_e32 v2, 7, v75
	v_lshl_add_u64 v[72:73], s[80:81], 0, v[72:73]
	v_and_b32_e32 v2, 0xffffff00, v2
	v_and_b32_e32 v3, 64, v76
	ds_read2_b32 v[6:7], v83 offset0:65 offset1:73
	ds_read2_b32 v[8:9], v83 offset1:8
	ds_read2_b32 v[10:11], v83 offset0:130 offset1:138
	ds_read2_b32 v[12:13], v83 offset0:195 offset1:203
	v_lshl_add_u64 v[70:71], v[72:73], 0, v[70:71]
	v_or3_b32 v2, v2, v67, v3
	v_ashrrev_i32_e32 v75, 31, v74
	v_cndmask_b32_e64 v26, v2, v76, s[8:9]
	v_lshl_add_u64 v[2:3], v[74:75], 1, v[70:71]
	v_mov_b32_e32 v67, v1
	v_add_u32_e32 v27, 0x400, v83
	ds_read2_b32 v[14:15], v27 offset0:4 offset1:12
	ds_read2_b32 v[16:17], v27 offset0:69 offset1:77
	ds_read2_b32 v[18:19], v27 offset0:134 offset1:142
	ds_read2_b32 v[20:21], v27 offset0:199 offset1:207
	v_lshl_add_u64 v[22:23], v[2:3], 0, v[66:67]
	s_waitcnt lgkmcnt(6)
	v_cvt_pk_bf16_f32 v2, v8, v6
	v_or_b32_e32 v6, v26, v82
	v_mul_lo_u32 v8, v69, v6
	v_mad_u64_u32 v[24:25], s[0:1], v68, v6, 0
	v_ashrrev_i32_e32 v6, 31, v26
	v_mul_lo_u32 v28, v68, v6
	v_add3_u32 v25, v25, v28, v8
	v_lshl_add_u64 v[24:25], v[24:25], 1, v[22:23]
	v_lshlrev_b64 v[128:129], 4, v[68:69]
	v_lshl_add_u64 v[126:127], v[24:25], 0, v[128:129]
	s_waitcnt lgkmcnt(4)
; #define LAS __attribute__((address_space(3)))
; __device__ __forceinline__ unsigned pk2(float lo, float hi) { unsigned r; asm("v_cvt_pk_bf16_f32 %0, %1, %2" : "=v"(r) : "v"(lo), "v"(hi)); return r; }
; __device__ __forceinline__ void p0_item(const float* W, const float* gain, int K, int N, bf16_t* WT, int mode, LAS float* scr, int item, int lane) {
;     ...
;     for (int j = 0; j < 8; ++j) { const int n = (lane >> 3) + 8 * j; const LAS float* s = scr + (8 * c) * 65 + n;
;         u32x4 o; o.x = pk2(s[0 * 65], s[1 * 65]); o.y = pk2(s[2 * 65], s[3 * 65]); o.z = pk2(s[4 * 65], s[5 * 65]); o.w = pk2(s[6 * 65], s[7 * 65]);
;         __builtin_nontemporal_store(o, (u32x4*)(WT + (size_t)(rbase + n) * K + k0 + 8 * c)); }
	v_cvt_pk_bf16_f32 v3, v10, v12
	s_waitcnt lgkmcnt(2)
	v_cvt_pk_bf16_f32 v4, v14, v16
	s_waitcnt lgkmcnt(0)
	v_cvt_pk_bf16_f32 v5, v18, v20
	global_store_dwordx4 v[24:25], v[2:5], off nt
	s_nop 1
	s_nop 0
	v_cvt_pk_bf16_f32 v2, v9, v7
	v_cvt_pk_bf16_f32 v3, v11, v13
	v_cvt_pk_bf16_f32 v4, v15, v17
	v_cvt_pk_bf16_f32 v5, v19, v21
	ds_read2_b32 v[8:9], v83 offset0:16 offset1:24
	ds_read2_b32 v[10:11], v83 offset0:81 offset1:89
	ds_read2_b32 v[12:13], v83 offset0:146 offset1:154
	ds_read2_b32 v[14:15], v83 offset0:211 offset1:219
	ds_read2_b32 v[16:17], v27 offset0:20 offset1:28
	ds_read2_b32 v[18:19], v27 offset0:85 offset1:93
	ds_read2_b32 v[20:21], v27 offset0:150 offset1:158
	ds_read2_b32 v[24:25], v27 offset0:215 offset1:223
	global_store_dwordx4 v[126:127], v[2:5], off nt
	v_lshl_add_u64 v[126:127], v[126:127], 0, v[128:129]
	s_waitcnt lgkmcnt(6)
	v_cvt_pk_bf16_f32 v2, v8, v10
	s_waitcnt lgkmcnt(4)
	v_cvt_pk_bf16_f32 v3, v12, v14
	s_waitcnt lgkmcnt(2)
	v_cvt_pk_bf16_f32 v4, v16, v18
	s_waitcnt lgkmcnt(0)
	v_cvt_pk_bf16_f32 v5, v20, v24
	global_store_dwordx4 v[126:127], v[2:5], off nt
	s_nop 1
	v_lshl_add_u64 v[126:127], v[126:127], 0, v[128:129]
	v_cvt_pk_bf16_f32 v2, v9, v11
	v_cvt_pk_bf16_f32 v3, v13, v15
	v_cvt_pk_bf16_f32 v4, v17, v19
	v_cvt_pk_bf16_f32 v5, v21, v25
	ds_read2_b32 v[8:9], v83 offset0:32 offset1:40
	ds_read2_b32 v[10:11], v83 offset0:97 offset1:105
	ds_read2_b32 v[12:13], v83 offset0:162 offset1:170
	ds_read2_b32 v[14:15], v83 offset0:227 offset1:235
	ds_read2_b32 v[16:17], v27 offset0:36 offset1:44
	ds_read2_b32 v[18:19], v27 offset0:101 offset1:109
	ds_read2_b32 v[20:21], v27 offset0:166 offset1:174
	ds_read2_b32 v[24:25], v27 offset0:231 offset1:239
	global_store_dwordx4 v[126:127], v[2:5], off nt
	v_lshl_add_u64 v[126:127], v[126:127], 0, v[128:129]
	s_waitcnt lgkmcnt(6)
	v_cvt_pk_bf16_f32 v2, v8, v10
	s_waitcnt lgkmcnt(4)
	v_cvt_pk_bf16_f32 v3, v12, v14
	s_waitcnt lgkmcnt(2)
	v_cvt_pk_bf16_f32 v4, v16, v18
	s_waitcnt lgkmcnt(0)
	v_cvt_pk_bf16_f32 v5, v20, v24
	global_store_dwordx4 v[126:127], v[2:5], off nt
	s_nop 1
	v_lshl_add_u64 v[126:127], v[126:127], 0, v[128:129]
	v_cvt_pk_bf16_f32 v2, v9, v11
	v_cvt_pk_bf16_f32 v3, v13, v15
	v_cvt_pk_bf16_f32 v4, v17, v19
	v_cvt_pk_bf16_f32 v5, v21, v25
	ds_read2_b32 v[8:9], v83 offset0:48 offset1:56
	ds_read2_b32 v[10:11], v83 offset0:113 offset1:121
	ds_read2_b32 v[12:13], v83 offset0:178 offset1:186
	ds_read2_b32 v[14:15], v83 offset0:243 offset1:251
	ds_read2_b32 v[16:17], v27 offset0:52 offset1:60
	ds_read2_b32 v[18:19], v27 offset0:117 offset1:125
	ds_read2_b32 v[20:21], v27 offset0:182 offset1:190
	ds_read2_b32 v[24:25], v27 offset0:247 offset1:255
	global_store_dwordx4 v[126:127], v[2:5], off nt
	v_lshl_add_u64 v[126:127], v[126:127], 0, v[128:129]
	s_waitcnt lgkmcnt(6)
	v_cvt_pk_bf16_f32 v2, v8, v10
	s_waitcnt lgkmcnt(4)
	v_cvt_pk_bf16_f32 v3, v12, v14
	s_waitcnt lgkmcnt(2)
	v_cvt_pk_bf16_f32 v4, v16, v18
	s_waitcnt lgkmcnt(0)
	v_cvt_pk_bf16_f32 v5, v20, v24
	global_store_dwordx4 v[126:127], v[2:5], off nt
	s_nop 1
	v_lshl_add_u64 v[126:127], v[126:127], 0, v[128:129]
	v_cvt_pk_bf16_f32 v2, v9, v11
	v_cvt_pk_bf16_f32 v3, v13, v15
	v_cvt_pk_bf16_f32 v4, v17, v19
	v_cvt_pk_bf16_f32 v5, v21, v25
	global_store_dwordx4 v[126:127], v[2:5], off nt
	v_readlane_b32 s0, v254, 60
	s_waitcnt lgkmcnt(0)
	s_nop 1
	v_add_u32_e32 v80, s0, v80
	v_cmp_le_i32_e32 vcc, s26, v80
	s_or_b64 s[6:7], vcc, s[6:7]
	s_andn2_b64 exec, exec, s[6:7]
	s_cbranch_execz .LBB0_355

; #define LAS __attribute__((address_space(3)))
; __device__ __forceinline__ unsigned pk2(float lo, float hi) { unsigned r; asm("v_cvt_pk_bf16_f32 %0, %1, %2" : "=v"(r) : "v"(lo), "v"(hi)); return r; }
; #define LDS_WAIT() asm volatile("s_waitcnt lgkmcnt(0)" ::: "memory")
; __device__ __forceinline__ void p0_item(const float* W, const float* gain, int K, int N, bf16_t* WT, int mode, LAS float* scr, int item, int lane) {
;     ...
;     for (int i = 0; i < 16; ++i) { LAS float* s = scr + (4 * i + kr) * 65 + nc; s[0] = v[i][0]; s[1] = v[i][1]; s[2] = v[i][2]; s[3] = v[i][3]; }
;     LDS_WAIT();
;     const int c = lane & 7;
;     const int rbase = (mode == 0) ? n0 : ((n0 >> 7) * 256 + (mode == 2 ? 128 : 0) + (n0 & 127));
; #pragma unroll
;     for (int j = 0; j < 8; ++j) { const int n = (lane >> 3) + 8 * j; const LAS float* s = scr + (8 * c) * 65 + n;
;         u32x4 o; o.x = pk2(s[0 * 65], s[1 * 65]); o.y = pk2(s[2 * 65], s[3 * 65]); o.z = pk2(s[4 * 65], s[5 * 65]); o.w = pk2(s[6 * 65], s[7 * 65]);
;         __builtin_nontemporal_store(o, (u32x4*)(WT + (size_t)(rbase + n) * K + k0 + 8 * c)); }
.LBB0_457:
	s_or_b64 exec, exec, s[10:11]
	s_waitcnt vmcnt(15)
	ds_write2_b32 v91, v6, v7 offset1:1
	ds_write2_b32 v91, v8, v9 offset0:2 offset1:3
	v_add_u32_e32 v6, 0x410, v91
	s_waitcnt vmcnt(14)
	ds_write2_b32 v6, v2, v3 offset1:1
	v_add_u32_e32 v2, 0x418, v91
	ds_write2_b32 v2, v4, v5 offset1:1
	v_add_u32_e32 v2, 0x820, v91
	s_waitcnt vmcnt(13)
	ds_write2_b32 v2, v14, v15 offset1:1
	v_add_u32_e32 v2, 0x828, v91
	ds_write2_b32 v2, v16, v17 offset1:1
	v_add_u32_e32 v2, 0xc30, v91
	s_waitcnt vmcnt(12)
	ds_write2_b32 v2, v10, v11 offset1:1
	v_add_u32_e32 v2, 0xc38, v91
	ds_write2_b32 v2, v12, v13 offset1:1
	v_add_u32_e32 v2, 0x1040, v91
	s_waitcnt vmcnt(11)
	ds_write2_b32 v2, v22, v23 offset1:1
	v_add_u32_e32 v2, 0x1048, v91
	ds_write2_b32 v2, v24, v25 offset1:1
	v_add_u32_e32 v2, 0x1450, v91
	s_waitcnt vmcnt(10)
	ds_write2_b32 v2, v18, v19 offset1:1
	v_add_u32_e32 v2, 0x1458, v91
	ds_write2_b32 v2, v20, v21 offset1:1
	v_add_u32_e32 v2, 0x1860, v91
	s_waitcnt vmcnt(9)
	ds_write2_b32 v2, v30, v31 offset1:1
	v_add_u32_e32 v2, 0x1868, v91
	ds_write2_b32 v2, v32, v33 offset1:1
	v_add_u32_e32 v2, 0x1c70, v91
	s_waitcnt vmcnt(8)
	ds_write2_b32 v2, v26, v27 offset1:1
	v_add_u32_e32 v2, 0x1c78, v91
	ds_write2_b32 v2, v28, v29 offset1:1
	v_add_u32_e32 v2, 0x2080, v91
	s_waitcnt vmcnt(7)
	ds_write2_b32 v2, v38, v39 offset1:1
	v_add_u32_e32 v2, 0x2088, v91
	ds_write2_b32 v2, v40, v41 offset1:1
	v_add_u32_e32 v2, 0x2490, v91
	s_waitcnt vmcnt(6)
	ds_write2_b32 v2, v34, v35 offset1:1
	v_add_u32_e32 v2, 0x2498, v91
	ds_write2_b32 v2, v36, v37 offset1:1
	v_add_u32_e32 v2, 0x28a0, v91
	s_waitcnt vmcnt(5)
	ds_write2_b32 v2, v46, v47 offset1:1
	v_add_u32_e32 v2, 0x28a8, v91
	ds_write2_b32 v2, v48, v49 offset1:1
	v_add_u32_e32 v2, 0x2cb0, v91
	s_waitcnt vmcnt(4)
	ds_write2_b32 v2, v42, v43 offset1:1
	v_add_u32_e32 v2, 0x2cb8, v91
	ds_write2_b32 v2, v44, v45 offset1:1
	v_add_u32_e32 v2, 0x30c0, v91
	s_waitcnt vmcnt(3)
	ds_write2_b32 v2, v54, v55 offset1:1
	v_add_u32_e32 v2, 0x30c8, v91
	ds_write2_b32 v2, v56, v57 offset1:1
	v_add_u32_e32 v2, 0x34d0, v91
	s_waitcnt vmcnt(2)
	ds_write2_b32 v2, v50, v51 offset1:1
	v_add_u32_e32 v2, 0x34d8, v91
	ds_write2_b32 v2, v52, v53 offset1:1
	v_add_u32_e32 v2, 0x38e0, v91
	s_waitcnt vmcnt(1)
	ds_write2_b32 v2, v62, v63 offset1:1
	v_add_u32_e32 v2, 0x38e8, v91
	ds_write2_b32 v2, v64, v65 offset1:1
	v_add_u32_e32 v2, 0x3cf0, v91
	s_waitcnt vmcnt(0)
	ds_write2_b32 v2, v58, v59 offset1:1
	v_add_u32_e32 v2, 0x3cf8, v91
	ds_write2_b32 v2, v60, v61 offset1:1
	v_cndmask_b32_e32 v72, 0, v228, vcc
	v_mov_b32_e32 v73, v1
	s_waitcnt lgkmcnt(0)
	v_lshlrev_b32_e32 v2, 7, v75
	v_lshl_add_u64 v[72:73], s[80:81], 0, v[72:73]
	v_and_b32_e32 v2, 0xffffff00, v2
	v_and_b32_e32 v3, 64, v76
	ds_read2_b32 v[6:7], v83 offset0:65 offset1:73
	ds_read2_b32 v[8:9], v83 offset1:8
	ds_read2_b32 v[10:11], v83 offset0:130 offset1:138
	ds_read2_b32 v[12:13], v83 offset0:195 offset1:203
	v_lshl_add_u64 v[70:71], v[72:73], 0, v[70:71]
	v_or3_b32 v2, v2, v67, v3
	v_ashrrev_i32_e32 v75, 31, v74
	v_cndmask_b32_e64 v26, v2, v76, s[8:9]
	v_lshl_add_u64 v[2:3], v[74:75], 1, v[70:71]
	v_mov_b32_e32 v67, v1
	v_add_u32_e32 v27, 0x400, v83
	ds_read2_b32 v[14:15], v27 offset0:4 offset1:12
	ds_read2_b32 v[16:17], v27 offset0:69 offset1:77
	ds_read2_b32 v[18:19], v27 offset0:134 offset1:142
	ds_read2_b32 v[20:21], v27 offset0:199 offset1:207
	v_lshl_add_u64 v[22:23], v[2:3], 0, v[66:67]
	s_waitcnt lgkmcnt(6)
	v_cvt_pk_bf16_f32 v2, v8, v6
	v_or_b32_e32 v6, v26, v82
	v_mul_lo_u32 v8, v69, v6
	v_mad_u64_u32 v[24:25], s[0:1], v68, v6, 0
	v_ashrrev_i32_e32 v6, 31, v26
	v_mul_lo_u32 v28, v68, v6
	v_add3_u32 v25, v25, v28, v8
	v_lshl_add_u64 v[24:25], v[24:25], 1, v[22:23]
	v_lshlrev_b64 v[128:129], 4, v[68:69]
	v_lshl_add_u64 v[126:127], v[24:25], 0, v[128:129]
	s_waitcnt lgkmcnt(4)
; #define LAS __attribute__((address_space(3)))
; __device__ __forceinline__ unsigned pk2(float lo, float hi) { unsigned r; asm("v_cvt_pk_bf16_f32 %0, %1, %2" : "=v"(r) : "v"(lo), "v"(hi)); return r; }
; __device__ __forceinline__ void p0_item(const float* W, const float* gain, int K, int N, bf16_t* WT, int mode, LAS float* scr, int item, int lane) {
;     ...
;     for (int j = 0; j < 8; ++j) { const int n = (lane >> 3) + 8 * j; const LAS float* s = scr + (8 * c) * 65 + n;
;         u32x4 o; o.x = pk2(s[0 * 65], s[1 * 65]); o.y = pk2(s[2 * 65], s[3 * 65]); o.z = pk2(s[4 * 65], s[5 * 65]); o.w = pk2(s[6 * 65], s[7 * 65]);
;         __builtin_nontemporal_store(o, (u32x4*)(WT + (size_t)(rbase + n) * K + k0 + 8 * c)); }
	v_cvt_pk_bf16_f32 v3, v10, v12
	s_waitcnt lgkmcnt(2)
	v_cvt_pk_bf16_f32 v4, v14, v16
	s_waitcnt lgkmcnt(0)
	v_cvt_pk_bf16_f32 v5, v18, v20
	global_store_dwordx4 v[24:25], v[2:5], off nt
	s_nop 1
	s_nop 0
	v_cvt_pk_bf16_f32 v2, v9, v7
	v_cvt_pk_bf16_f32 v3, v11, v13
	v_cvt_pk_bf16_f32 v4, v15, v17
	v_cvt_pk_bf16_f32 v5, v19, v21
	ds_read2_b32 v[8:9], v83 offset0:16 offset1:24
	ds_read2_b32 v[10:11], v83 offset0:81 offset1:89
	ds_read2_b32 v[12:13], v83 offset0:146 offset1:154
	ds_read2_b32 v[14:15], v83 offset0:211 offset1:219
	ds_read2_b32 v[16:17], v27 offset0:20 offset1:28
	ds_read2_b32 v[18:19], v27 offset0:85 offset1:93
	ds_read2_b32 v[20:21], v27 offset0:150 offset1:158
	ds_read2_b32 v[24:25], v27 offset0:215 offset1:223
	global_store_dwordx4 v[126:127], v[2:5], off nt
	v_lshl_add_u64 v[126:127], v[126:127], 0, v[128:129]
	s_waitcnt lgkmcnt(6)
	v_cvt_pk_bf16_f32 v2, v8, v10
	s_waitcnt lgkmcnt(4)
	v_cvt_pk_bf16_f32 v3, v12, v14
	s_waitcnt lgkmcnt(2)
	v_cvt_pk_bf16_f32 v4, v16, v18
	s_waitcnt lgkmcnt(0)
	v_cvt_pk_bf16_f32 v5, v20, v24
	global_store_dwordx4 v[126:127], v[2:5], off nt
	s_nop 1
	v_lshl_add_u64 v[126:127], v[126:127], 0, v[128:129]
	v_cvt_pk_bf16_f32 v2, v9, v11
	v_cvt_pk_bf16_f32 v3, v13, v15
	v_cvt_pk_bf16_f32 v4, v17, v19
	v_cvt_pk_bf16_f32 v5, v21, v25
	ds_read2_b32 v[8:9], v83 offset0:32 offset1:40
	ds_read2_b32 v[10:11], v83 offset0:97 offset1:105
	ds_read2_b32 v[12:13], v83 offset0:162 offset1:170
	ds_read2_b32 v[14:15], v83 offset0:227 offset1:235
	ds_read2_b32 v[16:17], v27 offset0:36 offset1:44
	ds_read2_b32 v[18:19], v27 offset0:101 offset1:109
	ds_read2_b32 v[20:21], v27 offset0:166 offset1:174
	ds_read2_b32 v[24:25], v27 offset0:231 offset1:239
	global_store_dwordx4 v[126:127], v[2:5], off nt
	v_lshl_add_u64 v[126:127], v[126:127], 0, v[128:129]
	s_waitcnt lgkmcnt(6)
	v_cvt_pk_bf16_f32 v2, v8, v10
	s_waitcnt lgkmcnt(4)
	v_cvt_pk_bf16_f32 v3, v12, v14
	s_waitcnt lgkmcnt(2)
	v_cvt_pk_bf16_f32 v4, v16, v18
	s_waitcnt lgkmcnt(0)
	v_cvt_pk_bf16_f32 v5, v20, v24
	global_store_dwordx4 v[126:127], v[2:5], off nt
	s_nop 1
	v_lshl_add_u64 v[126:127], v[126:127], 0, v[128:129]
	v_cvt_pk_bf16_f32 v2, v9, v11
	v_cvt_pk_bf16_f32 v3, v13, v15
	v_cvt_pk_bf16_f32 v4, v17, v19
	v_cvt_pk_bf16_f32 v5, v21, v25
	ds_read2_b32 v[8:9], v83 offset0:48 offset1:56
	ds_read2_b32 v[10:11], v83 offset0:113 offset1:121
	ds_read2_b32 v[12:13], v83 offset0:178 offset1:186
	ds_read2_b32 v[14:15], v83 offset0:243 offset1:251
	ds_read2_b32 v[16:17], v27 offset0:52 offset1:60
	ds_read2_b32 v[18:19], v27 offset0:117 offset1:125
	ds_read2_b32 v[20:21], v27 offset0:182 offset1:190
	ds_read2_b32 v[24:25], v27 offset0:247 offset1:255
	global_store_dwordx4 v[126:127], v[2:5], off nt
	v_lshl_add_u64 v[126:127], v[126:127], 0, v[128:129]
	s_waitcnt lgkmcnt(6)
	v_cvt_pk_bf16_f32 v2, v8, v10
	s_waitcnt lgkmcnt(4)
	v_cvt_pk_bf16_f32 v3, v12, v14
	s_waitcnt lgkmcnt(2)
	v_cvt_pk_bf16_f32 v4, v16, v18
	s_waitcnt lgkmcnt(0)
	v_cvt_pk_bf16_f32 v5, v20, v24
	global_store_dwordx4 v[126:127], v[2:5], off nt
	s_nop 1
	v_lshl_add_u64 v[126:127], v[126:127], 0, v[128:129]
	v_cvt_pk_bf16_f32 v2, v9, v11
	v_cvt_pk_bf16_f32 v3, v13, v15
	v_cvt_pk_bf16_f32 v4, v17, v19
	v_cvt_pk_bf16_f32 v5, v21, v25
	global_store_dwordx4 v[126:127], v[2:5], off nt
	v_readlane_b32 s0, v254, 11
	s_waitcnt lgkmcnt(0)
	s_nop 1
	v_add_u32_e32 v80, s0, v80
	s_movk_i32 s0, 0x74ff
	v_cmp_lt_i32_e32 vcc, s0, v80
	s_or_b64 s[6:7], vcc, s[6:7]
	s_andn2_b64 exec, exec, s[6:7]
	s_cbranch_execz .LBB0_496

; #define LAS __attribute__((address_space(3)))
; __device__ __forceinline__ unsigned pk2(float lo, float hi) { unsigned r; asm("v_cvt_pk_bf16_f32 %0, %1, %2" : "=v"(r) : "v"(lo), "v"(hi)); return r; }
; #define LDS_WAIT() asm volatile("s_waitcnt lgkmcnt(0)" ::: "memory")
; __device__ __forceinline__ void p0_item(const float* W, const float* gain, int K, int N, bf16_t* WT, int mode, LAS float* scr, int item, int lane) {
;     ...
;     for (int i = 0; i < 16; ++i) { LAS float* s = scr + (4 * i + kr) * 65 + nc; s[0] = v[i][0]; s[1] = v[i][1]; s[2] = v[i][2]; s[3] = v[i][3]; }
;     LDS_WAIT();
;     const int c = lane & 7;
;     const int rbase = (mode == 0) ? n0 : ((n0 >> 7) * 256 + (mode == 2 ? 128 : 0) + (n0 & 127));
; #pragma unroll
;     for (int j = 0; j < 8; ++j) { const int n = (lane >> 3) + 8 * j; const LAS float* s = scr + (8 * c) * 65 + n;
;         u32x4 o; o.x = pk2(s[0 * 65], s[1 * 65]); o.y = pk2(s[2 * 65], s[3 * 65]); o.z = pk2(s[4 * 65], s[5 * 65]); o.w = pk2(s[6 * 65], s[7 * 65]);
;         __builtin_nontemporal_store(o, (u32x4*)(WT + (size_t)(rbase + n) * K + k0 + 8 * c)); }
.LBB0_882:
	s_or_b64 exec, exec, s[10:11]
	s_waitcnt vmcnt(15)
	ds_write2_b32 v91, v6, v7 offset1:1
	ds_write2_b32 v91, v8, v9 offset0:2 offset1:3
	v_add_u32_e32 v6, 0x410, v91
	s_waitcnt vmcnt(14)
	ds_write2_b32 v6, v2, v3 offset1:1
	v_add_u32_e32 v2, 0x418, v91
	ds_write2_b32 v2, v4, v5 offset1:1
	v_add_u32_e32 v2, 0x820, v91
	s_waitcnt vmcnt(13)
	ds_write2_b32 v2, v14, v15 offset1:1
	v_add_u32_e32 v2, 0x828, v91
	ds_write2_b32 v2, v16, v17 offset1:1
	v_add_u32_e32 v2, 0xc30, v91
	s_waitcnt vmcnt(12)
	ds_write2_b32 v2, v10, v11 offset1:1
	v_add_u32_e32 v2, 0xc38, v91
	ds_write2_b32 v2, v12, v13 offset1:1
	v_add_u32_e32 v2, 0x1040, v91
	s_waitcnt vmcnt(11)
	ds_write2_b32 v2, v22, v23 offset1:1
	v_add_u32_e32 v2, 0x1048, v91
	ds_write2_b32 v2, v24, v25 offset1:1
	v_add_u32_e32 v2, 0x1450, v91
	s_waitcnt vmcnt(10)
	ds_write2_b32 v2, v18, v19 offset1:1
	v_add_u32_e32 v2, 0x1458, v91
	ds_write2_b32 v2, v20, v21 offset1:1
	v_add_u32_e32 v2, 0x1860, v91
	s_waitcnt vmcnt(9)
	ds_write2_b32 v2, v30, v31 offset1:1
	v_add_u32_e32 v2, 0x1868, v91
	ds_write2_b32 v2, v32, v33 offset1:1
	v_add_u32_e32 v2, 0x1c70, v91
	s_waitcnt vmcnt(8)
	ds_write2_b32 v2, v26, v27 offset1:1
	v_add_u32_e32 v2, 0x1c78, v91
	ds_write2_b32 v2, v28, v29 offset1:1
	v_add_u32_e32 v2, 0x2080, v91
	s_waitcnt vmcnt(7)
	ds_write2_b32 v2, v38, v39 offset1:1
	v_add_u32_e32 v2, 0x2088, v91
	ds_write2_b32 v2, v40, v41 offset1:1
	v_add_u32_e32 v2, 0x2490, v91
	s_waitcnt vmcnt(6)
	ds_write2_b32 v2, v34, v35 offset1:1
	v_add_u32_e32 v2, 0x2498, v91
	ds_write2_b32 v2, v36, v37 offset1:1
	v_add_u32_e32 v2, 0x28a0, v91
	s_waitcnt vmcnt(5)
	ds_write2_b32 v2, v46, v47 offset1:1
	v_add_u32_e32 v2, 0x28a8, v91
	ds_write2_b32 v2, v48, v49 offset1:1
	v_add_u32_e32 v2, 0x2cb0, v91
	s_waitcnt vmcnt(4)
	ds_write2_b32 v2, v42, v43 offset1:1
	v_add_u32_e32 v2, 0x2cb8, v91
	ds_write2_b32 v2, v44, v45 offset1:1
	v_add_u32_e32 v2, 0x30c0, v91
	s_waitcnt vmcnt(3)
	ds_write2_b32 v2, v54, v55 offset1:1
	v_add_u32_e32 v2, 0x30c8, v91
	ds_write2_b32 v2, v56, v57 offset1:1
	v_add_u32_e32 v2, 0x34d0, v91
	s_waitcnt vmcnt(2)
	ds_write2_b32 v2, v50, v51 offset1:1
	v_add_u32_e32 v2, 0x34d8, v91
	ds_write2_b32 v2, v52, v53 offset1:1
	v_add_u32_e32 v2, 0x38e0, v91
	s_waitcnt vmcnt(1)
	ds_write2_b32 v2, v62, v63 offset1:1
	v_add_u32_e32 v2, 0x38e8, v91
	ds_write2_b32 v2, v64, v65 offset1:1
	v_add_u32_e32 v2, 0x3cf0, v91
	s_waitcnt vmcnt(0)
	ds_write2_b32 v2, v58, v59 offset1:1
	v_add_u32_e32 v2, 0x3cf8, v91
	ds_write2_b32 v2, v60, v61 offset1:1
	v_cndmask_b32_e32 v72, 0, v228, vcc
	v_mov_b32_e32 v73, v1
	s_waitcnt lgkmcnt(0)
	v_lshlrev_b32_e32 v2, 7, v75
	v_lshl_add_u64 v[72:73], s[80:81], 0, v[72:73]
	v_and_b32_e32 v2, 0xffffff00, v2
	v_and_b32_e32 v3, 64, v76
	ds_read2_b32 v[6:7], v83 offset0:65 offset1:73
	ds_read2_b32 v[8:9], v83 offset1:8
	ds_read2_b32 v[10:11], v83 offset0:130 offset1:138
	ds_read2_b32 v[12:13], v83 offset0:195 offset1:203
	v_lshl_add_u64 v[70:71], v[72:73], 0, v[70:71]
	v_or3_b32 v2, v2, v67, v3
	v_ashrrev_i32_e32 v75, 31, v74
	v_cndmask_b32_e64 v26, v2, v76, s[8:9]
	v_lshl_add_u64 v[2:3], v[74:75], 1, v[70:71]
	v_mov_b32_e32 v67, v1
	v_add_u32_e32 v27, 0x400, v83
	ds_read2_b32 v[14:15], v27 offset0:4 offset1:12
	ds_read2_b32 v[16:17], v27 offset0:69 offset1:77
	ds_read2_b32 v[18:19], v27 offset0:134 offset1:142
	ds_read2_b32 v[20:21], v27 offset0:199 offset1:207
	v_lshl_add_u64 v[22:23], v[2:3], 0, v[66:67]
	s_waitcnt lgkmcnt(6)
	v_cvt_pk_bf16_f32 v2, v8, v6
	v_or_b32_e32 v6, v26, v82
	v_mul_lo_u32 v8, v69, v6
	v_mad_u64_u32 v[24:25], s[0:1], v68, v6, 0
	v_ashrrev_i32_e32 v6, 31, v26
	v_mul_lo_u32 v28, v68, v6
	v_add3_u32 v25, v25, v28, v8
	v_lshl_add_u64 v[24:25], v[24:25], 1, v[22:23]
	v_lshlrev_b64 v[128:129], 4, v[68:69]
	v_lshl_add_u64 v[126:127], v[24:25], 0, v[128:129]
	s_waitcnt lgkmcnt(4)
; #define LAS __attribute__((address_space(3)))
; __device__ __forceinline__ unsigned pk2(float lo, float hi) { unsigned r; asm("v_cvt_pk_bf16_f32 %0, %1, %2" : "=v"(r) : "v"(lo), "v"(hi)); return r; }
; __device__ __forceinline__ void p0_item(const float* W, const float* gain, int K, int N, bf16_t* WT, int mode, LAS float* scr, int item, int lane) {
;     ...
;     for (int j = 0; j < 8; ++j) { const int n = (lane >> 3) + 8 * j; const LAS float* s = scr + (8 * c) * 65 + n;
;         u32x4 o; o.x = pk2(s[0 * 65], s[1 * 65]); o.y = pk2(s[2 * 65], s[3 * 65]); o.z = pk2(s[4 * 65], s[5 * 65]); o.w = pk2(s[6 * 65], s[7 * 65]);
;         __builtin_nontemporal_store(o, (u32x4*)(WT + (size_t)(rbase + n) * K + k0 + 8 * c)); }
	v_cvt_pk_bf16_f32 v3, v10, v12
	s_waitcnt lgkmcnt(2)
	v_cvt_pk_bf16_f32 v4, v14, v16
	s_waitcnt lgkmcnt(0)
	v_cvt_pk_bf16_f32 v5, v18, v20
	global_store_dwordx4 v[24:25], v[2:5], off nt
	s_nop 1
	s_nop 0
	v_cvt_pk_bf16_f32 v2, v9, v7
	v_cvt_pk_bf16_f32 v3, v11, v13
	v_cvt_pk_bf16_f32 v4, v15, v17
	v_cvt_pk_bf16_f32 v5, v19, v21
	ds_read2_b32 v[8:9], v83 offset0:16 offset1:24
	ds_read2_b32 v[10:11], v83 offset0:81 offset1:89
	ds_read2_b32 v[12:13], v83 offset0:146 offset1:154
	ds_read2_b32 v[14:15], v83 offset0:211 offset1:219
	ds_read2_b32 v[16:17], v27 offset0:20 offset1:28
	ds_read2_b32 v[18:19], v27 offset0:85 offset1:93
	ds_read2_b32 v[20:21], v27 offset0:150 offset1:158
	ds_read2_b32 v[24:25], v27 offset0:215 offset1:223
	global_store_dwordx4 v[126:127], v[2:5], off nt
	v_lshl_add_u64 v[126:127], v[126:127], 0, v[128:129]
	s_waitcnt lgkmcnt(6)
	v_cvt_pk_bf16_f32 v2, v8, v10
	s_waitcnt lgkmcnt(4)
	v_cvt_pk_bf16_f32 v3, v12, v14
	s_waitcnt lgkmcnt(2)
	v_cvt_pk_bf16_f32 v4, v16, v18
	s_waitcnt lgkmcnt(0)
	v_cvt_pk_bf16_f32 v5, v20, v24
	global_store_dwordx4 v[126:127], v[2:5], off nt
	s_nop 1
	v_lshl_add_u64 v[126:127], v[126:127], 0, v[128:129]
	v_cvt_pk_bf16_f32 v2, v9, v11
	v_cvt_pk_bf16_f32 v3, v13, v15
	v_cvt_pk_bf16_f32 v4, v17, v19
	v_cvt_pk_bf16_f32 v5, v21, v25
	ds_read2_b32 v[8:9], v83 offset0:32 offset1:40
	ds_read2_b32 v[10:11], v83 offset0:97 offset1:105
	ds_read2_b32 v[12:13], v83 offset0:162 offset1:170
	ds_read2_b32 v[14:15], v83 offset0:227 offset1:235
	ds_read2_b32 v[16:17], v27 offset0:36 offset1:44
	ds_read2_b32 v[18:19], v27 offset0:101 offset1:109
	ds_read2_b32 v[20:21], v27 offset0:166 offset1:174
	ds_read2_b32 v[24:25], v27 offset0:231 offset1:239
	global_store_dwordx4 v[126:127], v[2:5], off nt
	v_lshl_add_u64 v[126:127], v[126:127], 0, v[128:129]
	s_waitcnt lgkmcnt(6)
	v_cvt_pk_bf16_f32 v2, v8, v10
	s_waitcnt lgkmcnt(4)
	v_cvt_pk_bf16_f32 v3, v12, v14
	s_waitcnt lgkmcnt(2)
	v_cvt_pk_bf16_f32 v4, v16, v18
	s_waitcnt lgkmcnt(0)
	v_cvt_pk_bf16_f32 v5, v20, v24
	global_store_dwordx4 v[126:127], v[2:5], off nt
	s_nop 1
	v_lshl_add_u64 v[126:127], v[126:127], 0, v[128:129]
	v_cvt_pk_bf16_f32 v2, v9, v11
	v_cvt_pk_bf16_f32 v3, v13, v15
	v_cvt_pk_bf16_f32 v4, v17, v19
	v_cvt_pk_bf16_f32 v5, v21, v25
	ds_read2_b32 v[8:9], v83 offset0:48 offset1:56
	ds_read2_b32 v[10:11], v83 offset0:113 offset1:121
	ds_read2_b32 v[12:13], v83 offset0:178 offset1:186
	ds_read2_b32 v[14:15], v83 offset0:243 offset1:251
	ds_read2_b32 v[16:17], v27 offset0:52 offset1:60
	ds_read2_b32 v[18:19], v27 offset0:117 offset1:125
	ds_read2_b32 v[20:21], v27 offset0:182 offset1:190
	ds_read2_b32 v[24:25], v27 offset0:247 offset1:255
	global_store_dwordx4 v[126:127], v[2:5], off nt
	v_lshl_add_u64 v[126:127], v[126:127], 0, v[128:129]
	s_waitcnt lgkmcnt(6)
	v_cvt_pk_bf16_f32 v2, v8, v10
	s_waitcnt lgkmcnt(4)
	v_cvt_pk_bf16_f32 v3, v12, v14
	s_waitcnt lgkmcnt(2)
	v_cvt_pk_bf16_f32 v4, v16, v18
	s_waitcnt lgkmcnt(0)
	v_cvt_pk_bf16_f32 v5, v20, v24
	global_store_dwordx4 v[126:127], v[2:5], off nt
	s_nop 1
	v_lshl_add_u64 v[126:127], v[126:127], 0, v[128:129]
	v_cvt_pk_bf16_f32 v2, v9, v11
	v_cvt_pk_bf16_f32 v3, v13, v15
	v_cvt_pk_bf16_f32 v4, v17, v19
	v_cvt_pk_bf16_f32 v5, v21, v25
	global_store_dwordx4 v[126:127], v[2:5], off nt
	v_readlane_b32 s0, v254, 53
	s_waitcnt lgkmcnt(0)
	s_nop 1
	v_add_u32_e32 v80, s0, v80
	s_mov_b32 s0, 0x94ff
	v_cmp_lt_i32_e32 vcc, s0, v80
	s_or_b64 s[6:7], vcc, s[6:7]
	s_andn2_b64 exec, exec, s[6:7]
	s_cbranch_execz .LBB0_921
